# stacked: counted lgkmcnt waits in all GEMM MFMA sections plus LDS-DMA issued ahead of the fragment reads in the in-proj loop
# speedup vs baseline: 1.0176x; 1.0021x over previous
; #define PG8_STAGE(bufoff, gbase, voff) do { _Pragma("unroll") for (int _i = 0; _i < 2; ++_i) \
;         __builtin_amdgcn_global_load_lds((const unsigned*)((const char*)(gbase) + (voff)[_i]), (LAS unsigned*)(lds + (bufoff) + ldsw + _i * 8192), 16, 0, 0); } while (0)
; #define PG8_LDA(dst, b, h) do { _Pragma("unroll") for (int m = 0; m < 4; ++m) _Pragma("unroll") for (int k = 0; k < 2; ++k) dst[m][k] = *(const LAS h8*)(lds + PG8_SA(b, h) + aoff + m * 2048 + k * 1024); } while (0)
; #define PG8_LDB(dst, b, h) do { _Pragma("unroll") for (int n = 0; n < 2; ++n) _Pragma("unroll") for (int k = 0; k < 2; ++k) dst[n][k] = *(const LAS h8*)(lds + PG8_SB(b, h) + boff + n * 2048 + k * 1024); } while (0)
; #define PG8_WAIT_L(n) asm volatile("s_waitcnt lgkmcnt(" #n ")" ::: "memory")
; #define PG8_BAR __builtin_amdgcn_s_barrier()
; #define PG8_SCHED __builtin_amdgcn_sched_barrier(0)
; template <class Epi>
; __device__ __forceinline__ void gemm_phase(LAS unsigned char* lds, const Gemm g, const StaticOrder& S, const Epi& E, const int tid) {
;     ...
;             PG8_LDB(B0, 0, 0); PG8_SCHED; PG8_LDA(At, 0, 0); PG8_STAGE(PG8_SA(1, 1), a1 + hstep, voffA);
;             PG8_WAIT_L(8); PG8_BAR; PG8_WAIT_L(0); PG8_MMA(0, 0, At, B0); PG8_BAR; PG8_SCHED;
;             PG8_LDB(B1, 0, 1); PG8_STAGE(PG8_SB(0, 0), b2, voffB);
;             PG8_BAR; PG8_WAIT_L(0); PG8_MMA(0, 1, At, B1); PG8_BAR;
;             PG8_LDA(At, 0, 1); PG8_STAGE(PG8_SA(0, 0), a2, voffA);
;             PG8_BAR; PG8_WAIT_L(0); PG8_MMA(1, 0, At, B0); PG8_BAR; PG8_SCHED;
.LBB0_332:
	s_add_u32 s18, s14, 0xfff80080
	s_addc_u32 s19, s15, -1
	s_add_i32 s55, 0, 0x10000
	v_add_u32_e32 v157, s55, v140
	s_cmp_eq_u32 s54, 28
	s_cselect_b32 s23, s9, s19
	s_cselect_b32 s22, s50, s18
	s_cselect_b32 s19, s1, s53
	s_cselect_b32 s18, s51, s52
	s_add_i32 m0, s39, 0xc000
	s_nop 0
	global_load_lds_dwordx4 v136, s[14:15]
	s_add_i32 m0, s39, 0xe000
	s_nop 0
	global_load_lds_dwordx4 v138, s[14:15]
	ds_read_b128 v[144:147], v157
	ds_read_b128 v[162:165], v157 offset:1024
	ds_read_b128 v[166:169], v157 offset:2048
	ds_read_b128 v[170:173], v157 offset:3072
	ds_read_b128 v[174:177], v143
	ds_read_b128 v[190:193], v143 offset:1024
	ds_read_b128 v[194:197], v143 offset:2048
	ds_read_b128 v[198:201], v143 offset:3072
	ds_read_b128 v[202:205], v143 offset:4096
	ds_read_b128 v[206:209], v143 offset:5120
	ds_read_b128 v[210:213], v143 offset:6144
	ds_read_b128 v[214:217], v143 offset:7168
	s_waitcnt lgkmcnt(8)
	s_barrier
	s_waitcnt lgkmcnt(7)
	v_mfma_f32_16x16x32_bf16 v[124:127], v[144:147], v[174:177], v[124:127]
	v_mfma_f32_16x16x32_bf16 v[128:131], v[166:169], v[174:177], v[128:131]
	s_waitcnt lgkmcnt(5)
	v_mfma_f32_16x16x32_bf16 v[108:111], v[144:147], v[194:197], v[108:111]
	v_mfma_f32_16x16x32_bf16 v[112:115], v[166:169], v[194:197], v[112:115]
	s_waitcnt lgkmcnt(3)
	v_mfma_f32_16x16x32_bf16 v[92:95], v[144:147], v[202:205], v[92:95]
	v_mfma_f32_16x16x32_bf16 v[96:99], v[166:169], v[202:205], v[96:99]
	s_waitcnt lgkmcnt(1)
	v_mfma_f32_16x16x32_bf16 v[76:79], v[144:147], v[210:213], v[76:79]
	v_mfma_f32_16x16x32_bf16 v[80:83], v[166:169], v[210:213], v[80:83]
	v_mfma_f32_16x16x32_bf16 v[124:127], v[162:165], v[190:193], v[124:127]
	v_mfma_f32_16x16x32_bf16 v[128:131], v[170:173], v[190:193], v[128:131]
	v_mfma_f32_16x16x32_bf16 v[108:111], v[162:165], v[198:201], v[108:111]
	v_mfma_f32_16x16x32_bf16 v[112:115], v[170:173], v[198:201], v[112:115]
	v_mfma_f32_16x16x32_bf16 v[92:95], v[162:165], v[206:209], v[92:95]
	v_mfma_f32_16x16x32_bf16 v[96:99], v[170:173], v[206:209], v[96:99]
	s_waitcnt lgkmcnt(0)
	v_mfma_f32_16x16x32_bf16 v[76:79], v[162:165], v[214:217], v[76:79]
	v_mfma_f32_16x16x32_bf16 v[80:83], v[170:173], v[214:217], v[80:83]
	s_barrier
	s_add_i32 s58, 0, 0x14000
	s_add_i32 s55, s55, s38
	v_add_u32_e32 v157, s58, v140
	v_lshl_add_u64 v[178:179], s[18:19], 0, v[2:3]
	s_mov_b32 m0, s55
	s_nop 0
	global_load_lds_dwordx4 v[178:179], off
	v_lshl_add_u64 v[234:235], s[18:19], 0, v[0:1]
	s_add_i32 m0, s55, 0x2000
	s_nop 0
	global_load_lds_dwordx4 v[234:235], off
	ds_read_b128 v[218:221], v157
	ds_read_b128 v[222:225], v157 offset:1024
	ds_read_b128 v[226:229], v157 offset:2048
	ds_read_b128 v[230:233], v157 offset:3072
	s_barrier
	s_waitcnt lgkmcnt(3)
	v_mfma_f32_16x16x32_bf16 v[116:119], v[218:221], v[174:177], v[116:119]
	s_waitcnt lgkmcnt(1)
	v_mfma_f32_16x16x32_bf16 v[120:123], v[226:229], v[174:177], v[120:123]
	v_mfma_f32_16x16x32_bf16 v[100:103], v[218:221], v[194:197], v[100:103]
	v_mfma_f32_16x16x32_bf16 v[104:107], v[226:229], v[194:197], v[104:107]
	v_mfma_f32_16x16x32_bf16 v[84:87], v[218:221], v[202:205], v[84:87]
	v_mfma_f32_16x16x32_bf16 v[88:91], v[226:229], v[202:205], v[88:91]
	v_mfma_f32_16x16x32_bf16 v[68:71], v[218:221], v[210:213], v[68:71]
	v_mfma_f32_16x16x32_bf16 v[72:75], v[226:229], v[210:213], v[72:75]
	v_mfma_f32_16x16x32_bf16 v[116:119], v[222:225], v[190:193], v[116:119]
	s_waitcnt lgkmcnt(0)
	v_mfma_f32_16x16x32_bf16 v[120:123], v[230:233], v[190:193], v[120:123]
	v_mfma_f32_16x16x32_bf16 v[100:103], v[222:225], v[198:201], v[100:103]
	v_mfma_f32_16x16x32_bf16 v[104:107], v[230:233], v[198:201], v[104:107]
	v_mfma_f32_16x16x32_bf16 v[84:87], v[222:225], v[206:209], v[84:87]
	v_mfma_f32_16x16x32_bf16 v[88:91], v[230:233], v[206:209], v[88:91]
	v_mfma_f32_16x16x32_bf16 v[68:71], v[222:225], v[214:217], v[68:71]
	v_mfma_f32_16x16x32_bf16 v[72:75], v[230:233], v[214:217], v[72:75]
	s_mov_b32 m0, s39
	v_lshl_add_u64 v[236:237], s[22:23], 0, v[134:135]
	s_barrier
	global_load_lds_dwordx4 v[236:237], off
	v_lshl_add_u64 v[238:239], s[22:23], 0, v[132:133]
	s_mov_b32 m0, s40
	s_nop 0
	global_load_lds_dwordx4 v[238:239], off
	ds_read_b128 v[174:177], v143 offset:16384
	ds_read_b128 v[190:193], v143 offset:17408
	ds_read_b128 v[194:197], v143 offset:18432
	ds_read_b128 v[198:201], v143 offset:19456
	ds_read_b128 v[202:205], v143 offset:20480
	ds_read_b128 v[206:209], v143 offset:21504
	ds_read_b128 v[210:213], v143 offset:22528
	ds_read_b128 v[214:217], v143 offset:23552
	s_barrier
	s_waitcnt lgkmcnt(7)
	v_mfma_f32_16x16x32_bf16 v[60:63], v[144:147], v[174:177], v[60:63]
	v_mfma_f32_16x16x32_bf16 v[64:67], v[166:169], v[174:177], v[64:67]
	s_waitcnt lgkmcnt(5)
	v_mfma_f32_16x16x32_bf16 v[44:47], v[144:147], v[194:197], v[44:47]
	v_mfma_f32_16x16x32_bf16 v[48:51], v[166:169], v[194:197], v[48:51]
	s_waitcnt lgkmcnt(3)
	v_mfma_f32_16x16x32_bf16 v[28:31], v[144:147], v[202:205], v[28:31]
	v_mfma_f32_16x16x32_bf16 v[32:35], v[166:169], v[202:205], v[32:35]
	s_waitcnt lgkmcnt(1)
	v_mfma_f32_16x16x32_bf16 v[12:15], v[144:147], v[210:213], v[12:15]
	v_mfma_f32_16x16x32_bf16 v[16:19], v[166:169], v[210:213], v[16:19]
	v_mfma_f32_16x16x32_bf16 v[60:63], v[162:165], v[190:193], v[60:63]
	v_mfma_f32_16x16x32_bf16 v[64:67], v[170:173], v[190:193], v[64:67]
	v_mfma_f32_16x16x32_bf16 v[44:47], v[162:165], v[198:201], v[44:47]
	v_mfma_f32_16x16x32_bf16 v[48:51], v[170:173], v[198:201], v[48:51]
	v_mfma_f32_16x16x32_bf16 v[28:31], v[162:165], v[206:209], v[28:31]
	v_mfma_f32_16x16x32_bf16 v[32:35], v[170:173], v[206:209], v[32:35]
	s_waitcnt lgkmcnt(0)
	v_mfma_f32_16x16x32_bf16 v[12:15], v[162:165], v[214:217], v[12:15]
	v_mfma_f32_16x16x32_bf16 v[16:19], v[170:173], v[214:217], v[16:19]
	s_barrier
; #define PG8_STAGE(bufoff, gbase, voff) do { _Pragma("unroll") for (int _i = 0; _i < 2; ++_i) \
;         __builtin_amdgcn_global_load_lds((const unsigned*)((const char*)(gbase) + (voff)[_i]), (LAS unsigned*)(lds + (bufoff) + ldsw + _i * 8192), 16, 0, 0); } while (0)
; #define PG8_LDA(dst, b, h) do { _Pragma("unroll") for (int m = 0; m < 4; ++m) _Pragma("unroll") for (int k = 0; k < 2; ++k) dst[m][k] = *(const LAS h8*)(lds + PG8_SA(b, h) + aoff + m * 2048 + k * 1024); } while (0)
; #define PG8_LDB(dst, b, h) do { _Pragma("unroll") for (int n = 0; n < 2; ++n) _Pragma("unroll") for (int k = 0; k < 2; ++k) dst[n][k] = *(const LAS h8*)(lds + PG8_SB(b, h) + boff + n * 2048 + k * 1024); } while (0)
; #define PG8_WAIT_V(n) asm volatile("s_waitcnt vmcnt(" #n ")" ::: "memory")
; #define PG8_WAIT_L(n) asm volatile("s_waitcnt lgkmcnt(" #n ")" ::: "memory")
; #define PG8_BAR __builtin_amdgcn_s_barrier()
; #define PG8_SCHED __builtin_amdgcn_sched_barrier(0)
; template <class Epi>
; __device__ __forceinline__ void gemm_phase(LAS unsigned char* lds, const Gemm g, const StaticOrder& S, const Epi& E, const int tid) {
;     ...
;             PG8_STAGE(PG8_SB(0, 1), b2 + hstepB, voffB);
;             PG8_WAIT_V(6); PG8_BAR; PG8_MMA(1, 1, At, B1); PG8_BAR;
;             PG8_LDB(B0, 1, 0); PG8_SCHED; PG8_LDA(At, 1, 0); PG8_STAGE(PG8_SA(0, 1), a2 + hstep, voffA);
;             PG8_WAIT_L(8); PG8_BAR; PG8_WAIT_L(0); PG8_MMA(0, 0, At, B0); PG8_BAR; PG8_SCHED;
;             PG8_LDB(B1, 1, 1); PG8_STAGE(PG8_SB(1, 0), b3, voffB);
;             PG8_BAR; PG8_WAIT_L(0); PG8_MMA(0, 1, At, B1); PG8_BAR;
;             PG8_LDA(At, 1, 1); PG8_STAGE(PG8_SA(1, 0), a3, voffA);
	s_add_u32 s56, s18, 0x20000
	s_addc_u32 s57, s19, 0
	s_add_i32 s55, s58, s38
	s_mov_b32 m0, s55
	s_nop 0
	global_load_lds_dwordx4 v2, s[56:57]
	s_add_i32 m0, s55, 0x2000
	s_nop 0
	global_load_lds_dwordx4 v0, s[56:57]
	s_waitcnt vmcnt(6)
	s_barrier
	v_mfma_f32_16x16x32_bf16 v[52:55], v[218:221], v[174:177], v[52:55]
	v_mfma_f32_16x16x32_bf16 v[56:59], v[226:229], v[174:177], v[56:59]
	v_mfma_f32_16x16x32_bf16 v[36:39], v[218:221], v[194:197], v[36:39]
	v_mfma_f32_16x16x32_bf16 v[40:43], v[226:229], v[194:197], v[40:43]
	v_mfma_f32_16x16x32_bf16 v[20:23], v[218:221], v[202:205], v[20:23]
	v_mfma_f32_16x16x32_bf16 v[24:27], v[226:229], v[202:205], v[24:27]
	v_mfma_f32_16x16x32_bf16 v[8:11], v[218:221], v[210:213], v[8:11]
	v_mfma_f32_16x16x32_bf16 v[4:7], v[226:229], v[210:213], v[4:7]
	v_mfma_f32_16x16x32_bf16 v[52:55], v[222:225], v[190:193], v[52:55]
	v_mfma_f32_16x16x32_bf16 v[56:59], v[230:233], v[190:193], v[56:59]
	v_mfma_f32_16x16x32_bf16 v[36:39], v[222:225], v[198:201], v[36:39]
	v_mfma_f32_16x16x32_bf16 v[40:43], v[230:233], v[198:201], v[40:43]
	v_mfma_f32_16x16x32_bf16 v[20:23], v[222:225], v[206:209], v[20:23]
	v_mfma_f32_16x16x32_bf16 v[24:27], v[230:233], v[206:209], v[24:27]
	v_mfma_f32_16x16x32_bf16 v[8:11], v[222:225], v[214:217], v[8:11]
	v_mfma_f32_16x16x32_bf16 v[4:7], v[230:233], v[214:217], v[4:7]
	s_add_i32 s55, 0, 0x18000
	v_add_u32_e32 v157, s55, v140
	s_barrier
	s_add_u32 s22, s22, 0x80000
	s_addc_u32 s23, s23, 0
	s_mov_b32 m0, s41
	s_nop 0
	global_load_lds_dwordx4 v134, s[22:23]
	s_mov_b32 m0, s42
	s_nop 0
	global_load_lds_dwordx4 v132, s[22:23]
	ds_read_b128 v[144:147], v157
	ds_read_b128 v[162:165], v157 offset:1024
	ds_read_b128 v[166:169], v157 offset:2048
	ds_read_b128 v[170:173], v157 offset:3072
	ds_read_b128 v[174:177], v143 offset:32768
	ds_read_b128 v[190:193], v143 offset:33792
	ds_read_b128 v[194:197], v143 offset:34816
	ds_read_b128 v[198:201], v143 offset:35840
	ds_read_b128 v[202:205], v143 offset:36864
	ds_read_b128 v[206:209], v143 offset:37888
	ds_read_b128 v[210:213], v143 offset:38912
	ds_read_b128 v[214:217], v143 offset:39936
	s_waitcnt lgkmcnt(8)
	s_barrier
	s_waitcnt lgkmcnt(7)
	v_mfma_f32_16x16x32_bf16 v[124:127], v[144:147], v[174:177], v[124:127]
	v_mfma_f32_16x16x32_bf16 v[128:131], v[166:169], v[174:177], v[128:131]
	s_waitcnt lgkmcnt(5)
	v_mfma_f32_16x16x32_bf16 v[108:111], v[144:147], v[194:197], v[108:111]
	v_mfma_f32_16x16x32_bf16 v[112:115], v[166:169], v[194:197], v[112:115]
	s_waitcnt lgkmcnt(3)
	v_mfma_f32_16x16x32_bf16 v[92:95], v[144:147], v[202:205], v[92:95]
	v_mfma_f32_16x16x32_bf16 v[96:99], v[166:169], v[202:205], v[96:99]
	s_waitcnt lgkmcnt(1)
	v_mfma_f32_16x16x32_bf16 v[76:79], v[144:147], v[210:213], v[76:79]
	v_mfma_f32_16x16x32_bf16 v[80:83], v[166:169], v[210:213], v[80:83]
	v_mfma_f32_16x16x32_bf16 v[124:127], v[162:165], v[190:193], v[124:127]
	v_mfma_f32_16x16x32_bf16 v[128:131], v[170:173], v[190:193], v[128:131]
	v_mfma_f32_16x16x32_bf16 v[108:111], v[162:165], v[198:201], v[108:111]
	v_mfma_f32_16x16x32_bf16 v[112:115], v[170:173], v[198:201], v[112:115]
	v_mfma_f32_16x16x32_bf16 v[92:95], v[162:165], v[206:209], v[92:95]
	v_mfma_f32_16x16x32_bf16 v[96:99], v[170:173], v[206:209], v[96:99]
	s_waitcnt lgkmcnt(0)
	v_mfma_f32_16x16x32_bf16 v[76:79], v[162:165], v[214:217], v[76:79]
	v_mfma_f32_16x16x32_bf16 v[80:83], v[170:173], v[214:217], v[80:83]
	s_barrier
	s_add_i32 s22, 0, 0x1c000
	s_add_i32 s23, s55, s38
	v_add_u32_e32 v157, s22, v140
	v_lshl_add_u64 v[178:179], v[178:179], 0, s[30:31]
	s_mov_b32 m0, s23
	s_nop 0
	global_load_lds_dwordx4 v[178:179], off
	v_lshl_add_u64 v[178:179], v[234:235], 0, s[30:31]
	s_add_i32 m0, s23, 0x2000
	s_nop 0
	global_load_lds_dwordx4 v[178:179], off
	ds_read_b128 v[218:221], v157
	ds_read_b128 v[222:225], v157 offset:1024
	ds_read_b128 v[226:229], v157 offset:2048
	ds_read_b128 v[230:233], v157 offset:3072
	s_barrier
	s_waitcnt lgkmcnt(3)
	v_mfma_f32_16x16x32_bf16 v[116:119], v[218:221], v[174:177], v[116:119]
	s_waitcnt lgkmcnt(1)
	v_mfma_f32_16x16x32_bf16 v[120:123], v[226:229], v[174:177], v[120:123]
	v_mfma_f32_16x16x32_bf16 v[100:103], v[218:221], v[194:197], v[100:103]
	v_mfma_f32_16x16x32_bf16 v[104:107], v[226:229], v[194:197], v[104:107]
	v_mfma_f32_16x16x32_bf16 v[84:87], v[218:221], v[202:205], v[84:87]
	v_mfma_f32_16x16x32_bf16 v[88:91], v[226:229], v[202:205], v[88:91]
	v_mfma_f32_16x16x32_bf16 v[68:71], v[218:221], v[210:213], v[68:71]
	v_mfma_f32_16x16x32_bf16 v[72:75], v[226:229], v[210:213], v[72:75]
	v_mfma_f32_16x16x32_bf16 v[116:119], v[222:225], v[190:193], v[116:119]
	s_waitcnt lgkmcnt(0)
	v_mfma_f32_16x16x32_bf16 v[120:123], v[230:233], v[190:193], v[120:123]
	v_mfma_f32_16x16x32_bf16 v[100:103], v[222:225], v[198:201], v[100:103]
	v_mfma_f32_16x16x32_bf16 v[104:107], v[230:233], v[198:201], v[104:107]
	v_mfma_f32_16x16x32_bf16 v[84:87], v[222:225], v[206:209], v[84:87]
	v_mfma_f32_16x16x32_bf16 v[88:91], v[230:233], v[206:209], v[88:91]
	v_mfma_f32_16x16x32_bf16 v[68:71], v[222:225], v[214:217], v[68:71]
	v_mfma_f32_16x16x32_bf16 v[72:75], v[230:233], v[214:217], v[72:75]
	s_mov_b32 m0, s43
	v_lshl_add_u64 v[178:179], v[236:237], 0, s[30:31]
	s_barrier
	global_load_lds_dwordx4 v[178:179], off
	v_lshl_add_u64 v[178:179], v[238:239], 0, s[30:31]
	s_mov_b32 m0, s46
	s_nop 0
	global_load_lds_dwordx4 v[178:179], off
	ds_read_b128 v[174:177], v143 offset:49152
	ds_read_b128 v[190:193], v143 offset:50176
	ds_read_b128 v[194:197], v143 offset:51200
	ds_read_b128 v[198:201], v143 offset:52224
	ds_read_b128 v[202:205], v143 offset:53248
	ds_read_b128 v[206:209], v143 offset:54272
	ds_read_b128 v[210:213], v143 offset:55296
	ds_read_b128 v[214:217], v143 offset:56320
	s_barrier
; #define PG8_STAGE(bufoff, gbase, voff) do { _Pragma("unroll") for (int _i = 0; _i < 2; ++_i) \
;         __builtin_amdgcn_global_load_lds((const unsigned*)((const char*)(gbase) + (voff)[_i]), (LAS unsigned*)(lds + (bufoff) + ldsw + _i * 8192), 16, 0, 0); } while (0)
; #define PG8_WAIT_V(n) asm volatile("s_waitcnt vmcnt(" #n ")" ::: "memory")
; #define PG8_WAIT_L(n) asm volatile("s_waitcnt lgkmcnt(" #n ")" ::: "memory")
; #define PG8_BAR __builtin_amdgcn_s_barrier()
; #define PG8_SCHED __builtin_amdgcn_sched_barrier(0)
; template <class Epi>
; __device__ __forceinline__ void gemm_phase(LAS unsigned char* lds, const Gemm g, const StaticOrder& S, const Epi& E, const int tid) {
;     ...
;             PG8_BAR; PG8_WAIT_L(0); PG8_MMA(1, 0, At, B0); PG8_BAR; PG8_SCHED;
;             PG8_STAGE(PG8_SB(1, 1), b3 + hstepB, voffB);
;             PG8_WAIT_V(6); PG8_BAR; PG8_MMA(1, 1, At, B1); PG8_BAR;
;     __device__ __forceinline__ void operator()(f32x4 (&acc)[2][2][4][2], const pg8::Unit& u, int wr, int wc, int fr, int fq) const {
;         const bool hi = fr >= 8;
;         const int row0 = u.pm * 256 + wr * 64 + (fr & 7), col = u.pn * 256 + wc * 64 + fq * 8 + (hi ? 32 : 0);
; #pragma unroll
;         for (int ai = 0; ai < 2; ++ai)
; #pragma unroll
;             for (int m = 0; m < 4; ++m) {
;                 const h8 x0 = pack8(acc[ai][0][m][0], acc[ai][0][m][1]), x1 = pack8(acc[ai][1][m][0], acc[ai][1][m][1]);
;                 const i32x4 snd = hi ? __builtin_bit_cast(i32x4, x0) : __builtin_bit_cast(i32x4, x1);
;                 i32x4 rcv;
; #pragma unroll
;                 for (int d = 0; d < 4; ++d) rcv[d] = __builtin_amdgcn_update_dpp(0, snd[d], 0x128  , 0xF, 0xF, false);
;                 const h8 rv = __builtin_bit_cast(h8, rcv);
;                 const h8 vA = hi ? rv : x0;
;                 const h8 vB = hi ? x1 : rv;
;                 half_t* rowp = O + (size_t)(row0 + ai * 128 + m * 16) * NIN + col;
;                 __builtin_nontemporal_store(vA, (h8*)rowp); __builtin_nontemporal_store(vB, (h8*)(rowp + (size_t)8 * NIN)); }
	s_waitcnt lgkmcnt(7)
	v_mfma_f32_16x16x32_bf16 v[60:63], v[144:147], v[174:177], v[60:63]
	v_mfma_f32_16x16x32_bf16 v[64:67], v[166:169], v[174:177], v[64:67]
	s_waitcnt lgkmcnt(5)
	v_mfma_f32_16x16x32_bf16 v[44:47], v[144:147], v[194:197], v[44:47]
	v_mfma_f32_16x16x32_bf16 v[48:51], v[166:169], v[194:197], v[48:51]
	s_waitcnt lgkmcnt(3)
	v_mfma_f32_16x16x32_bf16 v[28:31], v[144:147], v[202:205], v[28:31]
	v_mfma_f32_16x16x32_bf16 v[32:35], v[166:169], v[202:205], v[32:35]
	s_waitcnt lgkmcnt(1)
	v_mfma_f32_16x16x32_bf16 v[12:15], v[144:147], v[210:213], v[12:15]
	v_mfma_f32_16x16x32_bf16 v[16:19], v[166:169], v[210:213], v[16:19]
	v_mfma_f32_16x16x32_bf16 v[60:63], v[162:165], v[190:193], v[60:63]
	v_mfma_f32_16x16x32_bf16 v[64:67], v[170:173], v[190:193], v[64:67]
	v_mfma_f32_16x16x32_bf16 v[44:47], v[162:165], v[198:201], v[44:47]
	v_mfma_f32_16x16x32_bf16 v[48:51], v[170:173], v[198:201], v[48:51]
	v_mfma_f32_16x16x32_bf16 v[28:31], v[162:165], v[206:209], v[28:31]
	v_mfma_f32_16x16x32_bf16 v[32:35], v[170:173], v[206:209], v[32:35]
	s_waitcnt lgkmcnt(0)
	v_mfma_f32_16x16x32_bf16 v[12:15], v[162:165], v[214:217], v[12:15]
	v_mfma_f32_16x16x32_bf16 v[16:19], v[170:173], v[214:217], v[16:19]
	s_barrier
	s_add_u32 s18, s18, 0x20080
	s_addc_u32 s19, s19, 0
	s_add_i32 s22, s22, s38
	s_mov_b32 m0, s22
	s_nop 0
	global_load_lds_dwordx4 v2, s[18:19]
	v_lshl_add_u64 v[144:145], s[18:19], 0, v[0:1]
	s_add_i32 m0, s22, 0x2000
	s_nop 0
	global_load_lds_dwordx4 v[144:145], off
	s_waitcnt vmcnt(6)
	s_barrier
	v_mfma_f32_16x16x32_bf16 v[52:55], v[218:221], v[174:177], v[52:55]
	v_mfma_f32_16x16x32_bf16 v[56:59], v[226:229], v[174:177], v[56:59]
	v_mfma_f32_16x16x32_bf16 v[36:39], v[218:221], v[194:197], v[36:39]
	v_mfma_f32_16x16x32_bf16 v[40:43], v[226:229], v[194:197], v[40:43]
	v_mfma_f32_16x16x32_bf16 v[20:23], v[218:221], v[202:205], v[20:23]
	v_mfma_f32_16x16x32_bf16 v[24:27], v[226:229], v[202:205], v[24:27]
	v_mfma_f32_16x16x32_bf16 v[8:11], v[218:221], v[210:213], v[8:11]
	v_mfma_f32_16x16x32_bf16 v[4:7], v[226:229], v[210:213], v[4:7]
	v_mfma_f32_16x16x32_bf16 v[52:55], v[222:225], v[190:193], v[52:55]
	v_mfma_f32_16x16x32_bf16 v[56:59], v[230:233], v[190:193], v[56:59]
	v_mfma_f32_16x16x32_bf16 v[36:39], v[222:225], v[198:201], v[36:39]
	v_mfma_f32_16x16x32_bf16 v[40:43], v[230:233], v[198:201], v[40:43]
	v_mfma_f32_16x16x32_bf16 v[20:23], v[222:225], v[206:209], v[20:23]
	v_mfma_f32_16x16x32_bf16 v[24:27], v[230:233], v[206:209], v[24:27]
	v_mfma_f32_16x16x32_bf16 v[8:11], v[222:225], v[214:217], v[8:11]
	v_mfma_f32_16x16x32_bf16 v[4:7], v[230:233], v[214:217], v[4:7]
	s_add_i32 s54, s54, 2
	s_add_u32 s14, s14, 0x100
	s_addc_u32 s15, s15, 0
	s_add_u32 s52, s52, 0x100
	s_addc_u32 s53, s53, 0
	s_cmp_gt_u32 s54, 29
	s_barrier
	s_cbranch_scc0 .LBB0_332
	v_cvt_pk_f16_f32 v124, v124, v125
	v_cvt_pk_f16_f32 v116, v116, v117
	v_cvt_pk_f16_f32 v130, v130, v131
	v_cvt_pk_f16_f32 v131, v122, v123
	v_cvt_pk_f16_f32 v128, v128, v129
	v_cvt_pk_f16_f32 v129, v120, v121
	v_cvt_pk_f16_f32 v121, v126, v127
	v_cvt_pk_f16_f32 v118, v118, v119
	v_cndmask_b32_e64 v117, v116, v124, s[4:5]
	v_mov_b32_e32 v147, v3
	v_cndmask_b32_e64 v122, v131, v130, s[4:5]
	v_cndmask_b32_e64 v119, v118, v121, s[4:5]
	v_mov_b32_dpp v147, v117 row_ror:8 row_mask:0xf bank_mask:0xf
	v_mov_b32_e32 v117, v3
	v_mov_b32_e32 v125, v3
	v_lshl_or_b32 v144, s48, 8, v142
	v_cndmask_b32_e64 v120, v129, v128, s[4:5]
	v_mov_b32_dpp v117, v119 row_ror:8 row_mask:0xf bank_mask:0xf
	v_mov_b32_e32 v119, v3
	v_mov_b32_dpp v125, v122 row_ror:8 row_mask:0xf bank_mask:0xf
	v_lshl_add_u32 v146, s49, 8, v141
	v_ashrrev_i32_e32 v145, 31, v144
	v_mov_b32_dpp v119, v120 row_ror:8 row_mask:0xf bank_mask:0xf
	v_cndmask_b32_e64 v123, v130, v125, s[4:5]
	v_cndmask_b32_e64 v121, v121, v117, s[4:5]
	v_cndmask_b32_e64 v120, v124, v147, s[4:5]
	v_cndmask_b32_e64 v127, v125, v131, s[4:5]
	v_cndmask_b32_e64 v125, v117, v118, s[4:5]
	v_cndmask_b32_e64 v124, v147, v116, s[4:5]
	v_mov_b64_e32 v[116:117], s[36:37]
	v_cndmask_b32_e64 v122, v128, v119, s[4:5]
	v_cndmask_b32_e64 v126, v119, v129, s[4:5]
	v_mad_i64_i32 v[128:129], s[14:15], v146, s35, v[116:117]
	v_lshlrev_b64 v[118:119], 1, v[144:145]
	v_lshl_add_u64 v[128:129], v[128:129], 0, v[118:119]
	s_mov_b32 s1, 0x3c000
	global_store_dwordx4 v[128:129], v[120:123], off nt
	v_cvt_pk_f16_f32 v112, v112, v113
	v_cvt_pk_f16_f32 v104, v104, v105
	v_add_co_u32_e32 v120, vcc, s1, v128
	v_cvt_pk_f16_f32 v108, v108, v109
	s_nop 0
	v_addc_co_u32_e32 v121, vcc, 0, v129, vcc
	v_cvt_pk_f16_f32 v109, v100, v101
	global_store_dwordx4 v[120:121], v[124:127], off nt
	v_cvt_pk_f16_f32 v114, v114, v115
	v_cvt_pk_f16_f32 v106, v106, v107
	v_cndmask_b32_e64 v105, v104, v112, s[4:5]
	v_cndmask_b32_e64 v100, v109, v108, s[4:5]
	v_mov_b32_e32 v113, v3
	v_mov_b32_e32 v120, v3
	v_cndmask_b32_e64 v107, v106, v114, s[4:5]
	v_cvt_pk_f16_f32 v110, v110, v111
	v_cvt_pk_f16_f32 v111, v102, v103
	v_mov_b32_dpp v113, v100 row_ror:8 row_mask:0xf bank_mask:0xf
	v_mov_b32_dpp v120, v105 row_ror:8 row_mask:0xf bank_mask:0xf
	v_mov_b32_e32 v105, v3
	v_cndmask_b32_e64 v102, v111, v110, s[4:5]
	v_mov_b32_e32 v115, v3
	v_mov_b32_dpp v105, v107 row_ror:8 row_mask:0xf bank_mask:0xf
	v_cndmask_b32_e64 v100, v108, v113, s[4:5]
	v_or_b32_e32 v108, 16, v146
	v_mov_b32_dpp v115, v102 row_ror:8 row_mask:0xf bank_mask:0xf
	v_cndmask_b32_e64 v107, v105, v106, s[4:5]
	v_cndmask_b32_e64 v106, v120, v104, s[4:5]
	v_cndmask_b32_e64 v104, v113, v109, s[4:5]
	v_mad_i64_i32 v[108:109], s[14:15], v108, s35, v[116:117]
	v_cndmask_b32_e64 v103, v114, v105, s[4:5]
	v_cndmask_b32_e64 v102, v112, v120, s[4:5]
;     __device__ __forceinline__ void operator()(f32x4 (&acc)[2][2][4][2], const pg8::Unit& u, int wr, int wc, int fr, int fq) const {
;         const bool hi = fr >= 8;
;         const int row0 = u.pm * 256 + wr * 64 + (fr & 7), col = u.pn * 256 + wc * 64 + fq * 8 + (hi ? 32 : 0);
; #pragma unroll
;         for (int ai = 0; ai < 2; ++ai)
; #pragma unroll
;             for (int m = 0; m < 4; ++m) {
;                 const h8 x0 = pack8(acc[ai][0][m][0], acc[ai][0][m][1]), x1 = pack8(acc[ai][1][m][0], acc[ai][1][m][1]);
;                 const i32x4 snd = hi ? __builtin_bit_cast(i32x4, x0) : __builtin_bit_cast(i32x4, x1);
;                 i32x4 rcv;
; #pragma unroll
;                 for (int d = 0; d < 4; ++d) rcv[d] = __builtin_amdgcn_update_dpp(0, snd[d], 0x128  , 0xF, 0xF, false);
;                 const h8 rv = __builtin_bit_cast(h8, rcv);
;                 const h8 vA = hi ? rv : x0;
;                 const h8 vB = hi ? x1 : rv;
;                 half_t* rowp = O + (size_t)(row0 + ai * 128 + m * 16) * NIN + col;
;                 __builtin_nontemporal_store(vA, (h8*)rowp); __builtin_nontemporal_store(vB, (h8*)(rowp + (size_t)8 * NIN)); }
	v_cndmask_b32_e64 v101, v110, v115, s[4:5]
	v_lshl_add_u64 v[108:109], v[108:109], 0, v[118:119]
	global_store_dwordx4 v[108:109], v[100:103], off nt
	v_cndmask_b32_e64 v105, v115, v111, s[4:5]
	v_cvt_pk_f16_f32 v96, v96, v97
	v_add_co_u32_e32 v100, vcc, s1, v108
	v_cvt_pk_f16_f32 v88, v88, v89
	s_nop 0
	v_addc_co_u32_e32 v101, vcc, 0, v109, vcc
	v_cvt_pk_f16_f32 v92, v92, v93
	v_cvt_pk_f16_f32 v93, v84, v85
	global_store_dwordx4 v[100:101], v[104:107], off nt
	v_cvt_pk_f16_f32 v98, v98, v99
	v_cvt_pk_f16_f32 v90, v90, v91
	v_cndmask_b32_e64 v89, v88, v96, s[4:5]
	v_cndmask_b32_e64 v84, v93, v92, s[4:5]
	v_mov_b32_e32 v97, v3
	v_mov_b32_e32 v100, v3
	v_cndmask_b32_e64 v91, v90, v98, s[4:5]
	v_cvt_pk_f16_f32 v94, v94, v95
	v_cvt_pk_f16_f32 v95, v86, v87
	v_mov_b32_dpp v97, v84 row_ror:8 row_mask:0xf bank_mask:0xf
	v_mov_b32_dpp v100, v89 row_ror:8 row_mask:0xf bank_mask:0xf
	v_mov_b32_e32 v89, v3
	v_cndmask_b32_e64 v86, v95, v94, s[4:5]
	v_mov_b32_e32 v99, v3
	v_mov_b32_dpp v89, v91 row_ror:8 row_mask:0xf bank_mask:0xf
	v_cndmask_b32_e64 v84, v92, v97, s[4:5]
	v_or_b32_e32 v92, 32, v146
	v_mov_b32_dpp v99, v86 row_ror:8 row_mask:0xf bank_mask:0xf
	v_cndmask_b32_e64 v91, v89, v90, s[4:5]
	v_cndmask_b32_e64 v90, v100, v88, s[4:5]
	v_cndmask_b32_e64 v88, v97, v93, s[4:5]
	v_mad_i64_i32 v[92:93], s[14:15], v92, s35, v[116:117]
	v_cndmask_b32_e64 v87, v98, v89, s[4:5]
	v_cndmask_b32_e64 v86, v96, v100, s[4:5]
	v_cndmask_b32_e64 v85, v94, v99, s[4:5]
	v_lshl_add_u64 v[92:93], v[92:93], 0, v[118:119]
	global_store_dwordx4 v[92:93], v[84:87], off nt
	v_cndmask_b32_e64 v89, v99, v95, s[4:5]
	v_cvt_pk_f16_f32 v80, v80, v81
	v_add_co_u32_e32 v84, vcc, s1, v92
	v_cvt_pk_f16_f32 v72, v72, v73
	s_nop 0
	v_addc_co_u32_e32 v85, vcc, 0, v93, vcc
	v_cvt_pk_f16_f32 v76, v76, v77
	v_cvt_pk_f16_f32 v77, v68, v69
	global_store_dwordx4 v[84:85], v[88:91], off nt
	v_cvt_pk_f16_f32 v82, v82, v83
	v_cvt_pk_f16_f32 v74, v74, v75
	v_cndmask_b32_e64 v73, v72, v80, s[4:5]
	v_cndmask_b32_e64 v68, v77, v76, s[4:5]
	v_mov_b32_e32 v81, v3
	v_mov_b32_e32 v84, v3
	v_cndmask_b32_e64 v75, v74, v82, s[4:5]
	v_cvt_pk_f16_f32 v78, v78, v79
	v_cvt_pk_f16_f32 v79, v70, v71
	v_mov_b32_dpp v81, v68 row_ror:8 row_mask:0xf bank_mask:0xf
	v_mov_b32_dpp v84, v73 row_ror:8 row_mask:0xf bank_mask:0xf
	v_mov_b32_e32 v73, v3
	v_cndmask_b32_e64 v70, v79, v78, s[4:5]
	v_mov_b32_e32 v83, v3
	v_mov_b32_dpp v73, v75 row_ror:8 row_mask:0xf bank_mask:0xf
	v_cndmask_b32_e64 v68, v76, v81, s[4:5]
	v_or_b32_e32 v76, 48, v146
	v_mov_b32_dpp v83, v70 row_ror:8 row_mask:0xf bank_mask:0xf
	v_cndmask_b32_e64 v75, v73, v74, s[4:5]
	v_cndmask_b32_e64 v74, v84, v72, s[4:5]
	v_cndmask_b32_e64 v72, v81, v77, s[4:5]
	v_mad_i64_i32 v[76:77], s[14:15], v76, s35, v[116:117]
	v_cndmask_b32_e64 v71, v82, v73, s[4:5]
	v_cndmask_b32_e64 v70, v80, v84, s[4:5]
	v_cndmask_b32_e64 v69, v78, v83, s[4:5]
	v_lshl_add_u64 v[76:77], v[76:77], 0, v[118:119]
	global_store_dwordx4 v[76:77], v[68:71], off nt
	v_cndmask_b32_e64 v73, v83, v79, s[4:5]
	v_cvt_pk_f16_f32 v64, v64, v65
	v_add_co_u32_e32 v68, vcc, s1, v76
	v_cvt_pk_f16_f32 v56, v56, v57
	s_nop 0
	v_addc_co_u32_e32 v69, vcc, 0, v77, vcc
	global_store_dwordx4 v[68:69], v[72:75], off nt
	v_cvt_pk_f16_f32 v66, v66, v67
	v_cvt_pk_f16_f32 v58, v58, v59
	v_cndmask_b32_e64 v57, v56, v64, s[4:5]
	v_cvt_pk_f16_f32 v60, v60, v61
	v_cvt_pk_f16_f32 v61, v52, v53
	v_mov_b32_e32 v69, v3
	v_cndmask_b32_e64 v59, v58, v66, s[4:5]
	v_cvt_pk_f16_f32 v62, v62, v63
	v_cvt_pk_f16_f32 v63, v54, v55
	v_cndmask_b32_e64 v52, v61, v60, s[4:5]
	v_mov_b32_e32 v65, v3
	v_mov_b32_dpp v69, v57 row_ror:8 row_mask:0xf bank_mask:0xf
	v_mov_b32_e32 v57, v3
	v_add_u32_e32 v68, 0x80, v146
	v_cndmask_b32_e64 v54, v63, v62, s[4:5]
	v_mov_b32_dpp v65, v52 row_ror:8 row_mask:0xf bank_mask:0xf
	v_mov_b32_e32 v67, v3
	v_mov_b32_dpp v57, v59 row_ror:8 row_mask:0xf bank_mask:0xf
	v_cndmask_b32_e64 v52, v60, v65, s[4:5]
	v_mov_b32_dpp v67, v54 row_ror:8 row_mask:0xf bank_mask:0xf
	v_cndmask_b32_e64 v59, v57, v58, s[4:5]
	v_cndmask_b32_e64 v58, v69, v56, s[4:5]
	v_cndmask_b32_e64 v56, v65, v61, s[4:5]
	v_mad_i64_i32 v[60:61], s[14:15], v68, s35, v[116:117]
	v_cndmask_b32_e64 v55, v66, v57, s[4:5]
	v_cndmask_b32_e64 v54, v64, v69, s[4:5]
	v_cndmask_b32_e64 v53, v62, v67, s[4:5]
	v_lshl_add_u64 v[60:61], v[60:61], 0, v[118:119]
	global_store_dwordx4 v[60:61], v[52:55], off nt
	v_cndmask_b32_e64 v57, v67, v63, s[4:5]
	v_cvt_pk_f16_f32 v48, v48, v49
	v_add_co_u32_e32 v52, vcc, s1, v60
	v_cvt_pk_f16_f32 v40, v40, v41
	s_nop 0
	v_addc_co_u32_e32 v53, vcc, 0, v61, vcc
; #define PG8_WAIT_V(n) asm volatile("s_waitcnt vmcnt(" #n ")" ::: "memory")
; #define PG8_BAR __builtin_amdgcn_s_barrier()
; template <class Epi>
; __device__ __forceinline__ void gemm_phase(LAS unsigned char* lds, const Gemm g, const StaticOrder& S, const Epi& E, const int tid) {
;     ...
;         if (!has_next) break;
; #pragma unroll
;         for (int a = 0; a < 2; ++a)
; #pragma unroll
;             for (int b = 0; b < 2; ++b)
; #pragma unroll
;                 for (int m = 0; m < 4; ++m)
; #pragma unroll
;                     for (int n = 0; n < 2; ++n) acc[a][b][m][n] = (f32x4){0.f, 0.f, 0.f, 0.f};
;         cur = nxt; cA = nA; cB = nB; ++ui;
;     }
;     PG8_WAIT_V(0);
;     if (wr == 0) PG8_BAR;
;     PG8_BAR;
;     __device__ __forceinline__ void operator()(f32x4 (&acc)[2][2][4][2], const pg8::Unit& u, int wr, int wc, int fr, int fq) const {
;         const bool hi = fr >= 8;
;         const int row0 = u.pm * 256 + wr * 64 + (fr & 7), col = u.pn * 256 + wc * 64 + fq * 8 + (hi ? 32 : 0);
; #pragma unroll
;         for (int ai = 0; ai < 2; ++ai)
; #pragma unroll
;             for (int m = 0; m < 4; ++m) {
;                 const h8 x0 = pack8(acc[ai][0][m][0], acc[ai][0][m][1]), x1 = pack8(acc[ai][1][m][0], acc[ai][1][m][1]);
;                 const i32x4 snd = hi ? __builtin_bit_cast(i32x4, x0) : __builtin_bit_cast(i32x4, x1);
;                 i32x4 rcv;
; #pragma unroll
;                 for (int d = 0; d < 4; ++d) rcv[d] = __builtin_amdgcn_update_dpp(0, snd[d], 0x128  , 0xF, 0xF, false);
;                 const h8 rv = __builtin_bit_cast(h8, rcv);
;                 const h8 vA = hi ? rv : x0;
;                 const h8 vB = hi ? x1 : rv;
;                 half_t* rowp = O + (size_t)(row0 + ai * 128 + m * 16) * NIN + col;
;                 __builtin_nontemporal_store(vA, (h8*)rowp); __builtin_nontemporal_store(vB, (h8*)(rowp + (size_t)8 * NIN)); }
	v_cvt_pk_f16_f32 v44, v44, v45
	v_cvt_pk_f16_f32 v45, v36, v37
	global_store_dwordx4 v[52:53], v[56:59], off nt
	v_cvt_pk_f16_f32 v50, v50, v51
	v_cvt_pk_f16_f32 v42, v42, v43
	v_cndmask_b32_e64 v41, v40, v48, s[4:5]
	v_cndmask_b32_e64 v36, v45, v44, s[4:5]
	v_mov_b32_e32 v49, v3
	v_mov_b32_e32 v52, v3
	v_cndmask_b32_e64 v43, v42, v50, s[4:5]
	v_cvt_pk_f16_f32 v46, v46, v47
	v_cvt_pk_f16_f32 v47, v38, v39
	v_mov_b32_dpp v49, v36 row_ror:8 row_mask:0xf bank_mask:0xf
	v_mov_b32_dpp v52, v41 row_ror:8 row_mask:0xf bank_mask:0xf
	v_mov_b32_e32 v41, v3
	v_cndmask_b32_e64 v38, v47, v46, s[4:5]
	v_mov_b32_e32 v51, v3
	v_mov_b32_dpp v41, v43 row_ror:8 row_mask:0xf bank_mask:0xf
	v_cndmask_b32_e64 v36, v44, v49, s[4:5]
	v_add_u32_e32 v44, 0x90, v146
	v_mov_b32_dpp v51, v38 row_ror:8 row_mask:0xf bank_mask:0xf
	v_cndmask_b32_e64 v43, v41, v42, s[4:5]
	v_cndmask_b32_e64 v42, v52, v40, s[4:5]
	v_cndmask_b32_e64 v40, v49, v45, s[4:5]
	v_mad_i64_i32 v[44:45], s[14:15], v44, s35, v[116:117]
	v_cndmask_b32_e64 v39, v50, v41, s[4:5]
	v_cndmask_b32_e64 v38, v48, v52, s[4:5]
	v_cndmask_b32_e64 v37, v46, v51, s[4:5]
	v_lshl_add_u64 v[44:45], v[44:45], 0, v[118:119]
	global_store_dwordx4 v[44:45], v[36:39], off nt
	v_cndmask_b32_e64 v41, v51, v47, s[4:5]
	v_cvt_pk_f16_f32 v32, v32, v33
	v_add_co_u32_e32 v36, vcc, s1, v44
	v_cvt_pk_f16_f32 v24, v24, v25
	s_nop 0
	v_addc_co_u32_e32 v37, vcc, 0, v45, vcc
	v_cvt_pk_f16_f32 v28, v28, v29
	v_cvt_pk_f16_f32 v29, v20, v21
	global_store_dwordx4 v[36:37], v[40:43], off nt
	v_cvt_pk_f16_f32 v34, v34, v35
	v_cvt_pk_f16_f32 v26, v26, v27
	v_cndmask_b32_e64 v25, v24, v32, s[4:5]
	v_cndmask_b32_e64 v20, v29, v28, s[4:5]
	v_mov_b32_e32 v33, v3
	v_mov_b32_e32 v36, v3
	v_cndmask_b32_e64 v27, v26, v34, s[4:5]
	v_cvt_pk_f16_f32 v30, v30, v31
	v_cvt_pk_f16_f32 v31, v22, v23
	v_mov_b32_dpp v33, v20 row_ror:8 row_mask:0xf bank_mask:0xf
	v_mov_b32_dpp v36, v25 row_ror:8 row_mask:0xf bank_mask:0xf
	v_mov_b32_e32 v25, v3
	v_cvt_pk_f16_f32 v16, v16, v17
	v_cvt_pk_f16_f32 v17, v4, v5
	v_cvt_pk_f16_f32 v5, v14, v15
	v_cvt_pk_f16_f32 v14, v10, v11
	v_cvt_pk_f16_f32 v10, v12, v13
	v_cvt_pk_f16_f32 v8, v8, v9
	v_cndmask_b32_e64 v22, v31, v30, s[4:5]
	v_mov_b32_e32 v35, v3
	v_mov_b32_dpp v25, v27 row_ror:8 row_mask:0xf bank_mask:0xf
	v_cndmask_b32_e64 v20, v28, v33, s[4:5]
	v_add_u32_e32 v28, 0xa0, v146
	v_cndmask_b32_e64 v9, v8, v10, s[4:5]
	v_mov_b32_e32 v12, v3
	v_mov_b32_dpp v35, v22 row_ror:8 row_mask:0xf bank_mask:0xf
	v_cndmask_b32_e64 v27, v25, v26, s[4:5]
	v_cndmask_b32_e64 v26, v36, v24, s[4:5]
	v_cndmask_b32_e64 v24, v33, v29, s[4:5]
	v_mad_i64_i32 v[28:29], s[14:15], v28, s35, v[116:117]
	v_cvt_pk_f16_f32 v18, v18, v19
	v_cvt_pk_f16_f32 v19, v6, v7
	v_cndmask_b32_e64 v4, v17, v16, s[4:5]
	v_mov_b32_dpp v12, v9 row_ror:8 row_mask:0xf bank_mask:0xf
	v_mov_b32_e32 v13, v3
	v_cndmask_b32_e64 v23, v34, v25, s[4:5]
	v_cndmask_b32_e64 v22, v32, v36, s[4:5]
	v_cndmask_b32_e64 v21, v30, v35, s[4:5]
	v_lshl_add_u64 v[28:29], v[28:29], 0, v[118:119]
	v_cndmask_b32_e64 v6, v19, v18, s[4:5]
	v_cndmask_b32_e64 v7, v14, v5, s[4:5]
	v_mov_b32_e32 v9, v3
	v_mov_b32_dpp v13, v4 row_ror:8 row_mask:0xf bank_mask:0xf
	v_mov_b32_e32 v11, v3
	v_cndmask_b32_e64 v4, v10, v12, s[4:5]
	v_cndmask_b32_e64 v8, v12, v8, s[4:5]
	v_add_u32_e32 v12, 0xb0, v146
	global_store_dwordx4 v[28:29], v[20:23], off nt
	v_mov_b32_dpp v9, v7 row_ror:8 row_mask:0xf bank_mask:0xf
	v_mov_b32_dpp v11, v6 row_ror:8 row_mask:0xf bank_mask:0xf
	v_add_co_u32_e32 v20, vcc, s1, v28
	v_cndmask_b32_e64 v6, v16, v13, s[4:5]
	v_cndmask_b32_e64 v10, v13, v17, s[4:5]
	v_mad_i64_i32 v[12:13], s[14:15], v12, s35, v[116:117]
	v_addc_co_u32_e32 v21, vcc, 0, v29, vcc
	v_cndmask_b32_e64 v7, v18, v11, s[4:5]
	v_cndmask_b32_e64 v5, v5, v9, s[4:5]
	v_lshl_add_u64 v[12:13], v[12:13], 0, v[118:119]
	global_store_dwordx4 v[12:13], v[4:7], off nt
	v_cndmask_b32_e64 v25, v35, v31, s[4:5]
	v_cndmask_b32_e64 v11, v11, v19, s[4:5]
	v_add_co_u32_e32 v4, vcc, 0x3c000, v12
	v_cndmask_b32_e64 v9, v9, v14, s[4:5]
	s_nop 0
	v_addc_co_u32_e32 v5, vcc, 0, v13, vcc
	s_and_b64 vcc, exec, s[6:7]
	s_mov_b32 s48, s0
	s_mov_b32 s49, s8
	s_mov_b64 s[18:19], s[12:13]
	s_mov_b64 s[14:15], s[10:11]
	global_store_dwordx4 v[20:21], v[24:27], off nt
	global_store_dwordx4 v[4:5], v[8:11], off nt
	s_cbranch_vccz .LBB0_329
	s_waitcnt vmcnt(0)
	v_readlane_b32 s42, v251, 7
	v_readlane_b32 s46, v251, 9
	v_readlane_b32 s48, v251, 13
	s_cmpk_gt_u32 s20, 0xff
	v_readlane_b32 s43, v251, 8
	v_readlane_b32 s47, v251, 10
	v_readlane_b32 s49, v251, 14
	s_cbranch_scc1 .LBB0_336
	s_barrier
